# v26 with non-aligned unit epilogues (experiment)
# baseline (speedup 1.0000x reference)
.LBB0_229:
	s_cmp_gt_i32 s6, -1
	s_mov_b64 s[36:37], -1
	s_cbranch_scc0 .LBB0_224

.LBB0_232:
	s_andn2_b64 vcc, exec, s[12:13]
	s_cbranch_vccnz .LBB0_209
	s_branch .LBB0_209
.LBB0_234:
	s_waitcnt vmcnt(0)
	s_and_b64 vcc, exec, s[18:19]
	s_cbranch_vccz .Lnaep_9
	s_barrier
.Lnaep_9:
	s_barrier
.LBB0_235:
	v_readlane_b32 s2, v249, 11
	v_readlane_b32 s3, v249, 12
	s_cmp_eq_u32 s3, 3
	s_cselect_b64 s[2:3], -1, 0
	s_or_b64 s[0:1], s[2:3], s[0:1]
	s_and_b64 vcc, exec, s[0:1]
	s_cbranch_vccnz .LBB0_285
	s_waitcnt vmcnt(0)
	v_cmp_eq_u32_e32 vcc, 0, v0
	s_waitcnt vmcnt(0)
	s_barrier
	s_and_saveexec_b64 s[0:1], vcc
	s_cbranch_execz .LBB0_284
	v_mov_b32_e32 v2, s87
	s_waitcnt vmcnt(0) expcnt(0) lgkmcnt(0)
	ds_read_b32 v4, v2
	ds_read_b32 v2, v2 offset:4
	s_waitcnt lgkmcnt(1)
	v_cmp_ne_u32_e32 vcc, 0, v4
	s_cbranch_vccnz .LBB0_252
	v_readlane_b32 s4, v249, 1
	v_readlane_b32 s5, v249, 2
	s_load_dwordx2 s[2:3], s[4:5], 0x4
	s_add_u32 s4, s82, 0x4200
	s_addc_u32 s5, s83, 0
	s_add_u32 s6, s82, 0x4400
	s_addc_u32 s7, s83, 0
	s_add_u32 s12, s82, 0x4500
	s_addc_u32 s13, s83, 0
	s_add_u32 s16, s82, 0x4600
	s_addc_u32 s17, s83, 0
	s_add_u32 s18, s82, 0x4700
	s_addc_u32 s19, s83, 0
	s_add_u32 s20, s82, 0x4800
	s_addc_u32 s21, s83, 0
	s_add_u32 s22, s82, 0x4900
	s_addc_u32 s23, s83, 0
	s_add_u32 s24, s82, 0x4a00
	s_addc_u32 s25, s83, 0
	s_add_u32 s26, s82, 0x4b00
	s_addc_u32 s27, s83, 0
	s_add_u32 s28, s82, 0x4c00
	s_addc_u32 s29, s83, 0
	s_add_u32 s30, s82, 0x4d00
	s_addc_u32 s31, s83, 0
	s_add_u32 s34, s82, 0x4e00
	s_addc_u32 s35, s83, 0
	s_add_u32 s36, s82, 0x4f00
	s_addc_u32 s37, s83, 0
	s_add_u32 s38, s82, 0x5000
	s_addc_u32 s39, s83, 0
	s_add_u32 s40, s82, 0x5100
	s_addc_u32 s41, s83, 0
	s_add_u32 s42, s82, 0x5200
	s_addc_u32 s43, s83, 0
	s_waitcnt lgkmcnt(0)
	s_mul_i32 s2, s2, s90
	s_add_u32 s44, s82, 0x5300
	s_mul_i32 s2, s2, s3
	s_addc_u32 s45, s83, 0
	s_mov_b32 s3, 1
	v_mov_b32_e32 v18, 0
	s_branch .LBB0_240

.LBB0_365:
	s_cmp_gt_i32 s6, -1
	s_mov_b64 s[28:29], -1
	s_cbranch_scc0 .LBB0_360

.LBB0_371:
	s_waitcnt vmcnt(0)
	s_and_b64 vcc, exec, s[20:21]
	s_cbranch_vccz .Lnaep_8
	s_barrier
.Lnaep_8:
	s_barrier
.LBB0_372:
	v_readlane_b32 s0, v249, 11
	v_readlane_b32 s1, v249, 12
	s_cmp_eq_u32 s1, 5
	s_cselect_b64 s[0:1], -1, 0
	s_or_b64 s[0:1], s[0:1], s[4:5]
	s_and_b64 vcc, exec, s[0:1]
	s_cbranch_vccnz .LBB0_422
	s_waitcnt vmcnt(0)
	v_cmp_eq_u32_e32 vcc, 0, v0
	s_waitcnt vmcnt(0)
	s_barrier
	s_and_saveexec_b64 s[0:1], vcc
	s_cbranch_execz .LBB0_421
	v_mov_b32_e32 v2, s87
	s_waitcnt vmcnt(0) expcnt(0) lgkmcnt(0)
	ds_read_b32 v4, v2
	ds_read_b32 v2, v2 offset:4
	s_waitcnt lgkmcnt(1)
	v_cmp_ne_u32_e32 vcc, 0, v4
	s_cbranch_vccnz .LBB0_389
	v_readlane_b32 s4, v249, 1
	v_readlane_b32 s5, v249, 2
	s_load_dwordx2 s[2:3], s[4:5], 0x4
	s_add_u32 s4, s82, 0x4200
	s_addc_u32 s5, s83, 0
	s_add_u32 s6, s82, 0x4400
	s_addc_u32 s7, s83, 0
	s_add_u32 s12, s82, 0x4500
	s_addc_u32 s13, s83, 0
	s_add_u32 s16, s82, 0x4600
	s_addc_u32 s17, s83, 0
	s_add_u32 s18, s82, 0x4700
	s_addc_u32 s19, s83, 0
	s_add_u32 s20, s82, 0x4800
	s_addc_u32 s21, s83, 0
	s_add_u32 s22, s82, 0x4900
	s_addc_u32 s23, s83, 0
	s_add_u32 s24, s82, 0x4a00
	s_addc_u32 s25, s83, 0
	s_add_u32 s26, s82, 0x4b00
	s_addc_u32 s27, s83, 0
	s_add_u32 s28, s82, 0x4c00
	s_addc_u32 s29, s83, 0
	s_add_u32 s30, s82, 0x4d00
	s_addc_u32 s31, s83, 0
	s_add_u32 s34, s82, 0x4e00
	s_addc_u32 s35, s83, 0
	s_add_u32 s36, s82, 0x4f00
	s_addc_u32 s37, s83, 0
	s_add_u32 s38, s82, 0x5000
	s_addc_u32 s39, s83, 0
	s_add_u32 s40, s82, 0x5100
	s_addc_u32 s41, s83, 0
	s_add_u32 s42, s82, 0x5200
	s_addc_u32 s43, s83, 0
	s_waitcnt lgkmcnt(0)
	s_mul_i32 s2, s2, s90
	s_add_u32 s44, s82, 0x5300
	s_mul_i32 s2, s2, s3
	s_addc_u32 s45, s83, 0
	s_mov_b32 s3, 1
	v_mov_b32_e32 v18, 0
	s_branch .LBB0_377

.LBB0_1130:
	s_cmp_gt_i32 s6, -1
	s_mov_b64 s[30:31], -1
	s_cbranch_scc0 .LBB0_1125

.LBB0_1133:
	s_andn2_b64 vcc, exec, s[8:9]
	s_cbranch_vccnz .LBB0_1111
	s_branch .LBB0_1111

.LBB0_1136:
	s_waitcnt vmcnt(0)
	s_and_b64 vcc, exec, s[14:15]
	s_cbranch_vccz .Lnaep_7
	s_barrier
.Lnaep_7:
	s_barrier
.LBB0_1137:
	v_readlane_b32 s0, v249, 11
	v_readlane_b32 s1, v249, 12
	s_cmp_eq_u32 s1, 13
	s_cselect_b64 s[0:1], -1, 0
	s_or_b64 s[0:1], s[0:1], s[4:5]
	s_and_b64 vcc, exec, s[0:1]
	s_cbranch_vccnz .LBB0_1187
	s_waitcnt vmcnt(0)
	v_cmp_eq_u32_e32 vcc, 0, v0
	s_waitcnt vmcnt(0)
	s_barrier
	s_and_saveexec_b64 s[0:1], vcc
	s_cbranch_execz .LBB0_1186
	v_mov_b32_e32 v1, s87
	s_waitcnt vmcnt(0) expcnt(0) lgkmcnt(0)
	ds_read_b32 v3, v1
	ds_read_b32 v1, v1 offset:4
	s_waitcnt lgkmcnt(1)
	v_cmp_ne_u32_e32 vcc, 0, v3
	s_cbranch_vccnz .LBB0_1154
	v_readlane_b32 s4, v249, 1
	v_readlane_b32 s5, v249, 2
	s_load_dwordx2 s[2:3], s[4:5], 0x4
	s_add_u32 s4, s82, 0x4200
	s_addc_u32 s5, s83, 0
	s_add_u32 s6, s82, 0x4400
	s_addc_u32 s7, s83, 0
	s_add_u32 s8, s82, 0x4500
	s_addc_u32 s9, s83, 0
	s_add_u32 s10, s82, 0x4600
	s_addc_u32 s11, s83, 0
	s_add_u32 s12, s82, 0x4700
	s_addc_u32 s13, s83, 0
	s_add_u32 s14, s82, 0x4800
	s_addc_u32 s15, s83, 0
	s_add_u32 s16, s82, 0x4900
	s_addc_u32 s17, s83, 0
	s_add_u32 s18, s82, 0x4a00
	s_addc_u32 s19, s83, 0
	s_add_u32 s20, s82, 0x4b00
	s_addc_u32 s21, s83, 0
	s_add_u32 s22, s82, 0x4c00
	s_addc_u32 s23, s83, 0
	s_add_u32 s24, s82, 0x4d00
	s_addc_u32 s25, s83, 0
	s_add_u32 s26, s82, 0x4e00
	s_addc_u32 s27, s83, 0
	s_add_u32 s28, s82, 0x4f00
	s_addc_u32 s29, s83, 0
	s_add_u32 s30, s82, 0x5000
	s_addc_u32 s31, s83, 0
	s_add_u32 s34, s82, 0x5100
	s_addc_u32 s35, s83, 0
	s_add_u32 s36, s82, 0x5200
	s_addc_u32 s37, s83, 0
	s_waitcnt lgkmcnt(0)
	s_mul_i32 s2, s2, s90
	s_add_u32 s38, s82, 0x5300
	s_mul_i32 s2, s2, s3
	s_addc_u32 s39, s83, 0
	s_mov_b32 s3, 1
	v_mov_b32_e32 v17, 0
	s_branch .LBB0_1142

.LBB0_1328:
	s_waitcnt vmcnt(0)
	s_and_b64 vcc, exec, s[12:13]
	s_cbranch_vccz .Lnaep_6
	s_barrier
.Lnaep_6:
	s_barrier
.LBB0_1329:
	v_readlane_b32 s2, v249, 11
	v_readlane_b32 s3, v249, 12
	s_cmp_eq_u32 s3, 16
	s_cselect_b64 s[2:3], -1, 0
	s_or_b64 s[0:1], s[2:3], s[0:1]
	s_and_b64 vcc, exec, s[0:1]
	s_cbranch_vccnz .LBB0_1379
	s_waitcnt vmcnt(0)
	v_cmp_eq_u32_e32 vcc, 0, v0
	s_waitcnt vmcnt(0)
	s_barrier
	s_and_saveexec_b64 s[0:1], vcc
	s_cbranch_execz .LBB0_1378
	v_mov_b32_e32 v1, s87
	s_waitcnt vmcnt(0) expcnt(0) lgkmcnt(0)
	ds_read_b32 v3, v1
	ds_read_b32 v1, v1 offset:4
	s_waitcnt lgkmcnt(1)
	v_cmp_ne_u32_e32 vcc, 0, v3
	s_cbranch_vccnz .LBB0_1346
	v_readlane_b32 s4, v249, 1
	v_readlane_b32 s5, v249, 2
	s_load_dwordx2 s[2:3], s[4:5], 0x4
	s_add_u32 s4, s82, 0x4200
	s_addc_u32 s5, s83, 0
	s_add_u32 s6, s82, 0x4400
	s_addc_u32 s7, s83, 0
	s_add_u32 s8, s82, 0x4500
	s_addc_u32 s9, s83, 0
	s_add_u32 s10, s82, 0x4600
	s_addc_u32 s11, s83, 0
	s_add_u32 s12, s82, 0x4700
	s_addc_u32 s13, s83, 0
	s_add_u32 s14, s82, 0x4800
	s_addc_u32 s15, s83, 0
	s_add_u32 s16, s82, 0x4900
	s_addc_u32 s17, s83, 0
	s_add_u32 s18, s82, 0x4a00
	s_addc_u32 s19, s83, 0
	s_add_u32 s20, s82, 0x4b00
	s_addc_u32 s21, s83, 0
	s_add_u32 s22, s82, 0x4c00
	s_addc_u32 s23, s83, 0
	s_add_u32 s24, s82, 0x4d00
	s_addc_u32 s25, s83, 0
	s_add_u32 s26, s82, 0x4e00
	s_addc_u32 s27, s83, 0
	s_add_u32 s28, s82, 0x4f00
	s_addc_u32 s29, s83, 0
	s_add_u32 s30, s82, 0x5000
	s_addc_u32 s31, s83, 0
	s_add_u32 s34, s82, 0x5100
	s_addc_u32 s35, s83, 0
	s_add_u32 s36, s82, 0x5200
	s_addc_u32 s37, s83, 0
	s_waitcnt lgkmcnt(0)
	s_mul_i32 s2, s2, s90
	s_add_u32 s38, s82, 0x5300
	s_mul_i32 s2, s2, s3
	s_addc_u32 s39, s83, 0
	s_mov_b32 s3, 1
	v_mov_b32_e32 v17, 0
	s_branch .LBB0_1334

.LBB0_1459:
	s_cmp_gt_i32 s6, -1
	s_mov_b64 s[22:23], -1
	s_cbranch_scc0 .LBB0_1454

.Lnaep_5:
	s_barrier
.LBB0_1466:
	v_readlane_b32 s0, v249, 11
	v_readlane_b32 s1, v249, 12
	s_cmp_eq_u32 s1, 18
	s_cselect_b64 s[0:1], -1, 0
	s_or_b64 s[0:1], s[0:1], s[4:5]
	s_and_b64 vcc, exec, s[0:1]
	s_cbranch_vccnz .LBB0_1516
	s_waitcnt vmcnt(0)
	v_cmp_eq_u32_e32 vcc, 0, v0
	s_waitcnt vmcnt(0)
	s_barrier
	s_and_saveexec_b64 s[0:1], vcc
	s_cbranch_execz .LBB0_1515
	v_mov_b32_e32 v1, s87
	s_waitcnt vmcnt(0) expcnt(0) lgkmcnt(0)
	ds_read_b32 v3, v1
	ds_read_b32 v1, v1 offset:4
	s_waitcnt lgkmcnt(1)
	v_cmp_ne_u32_e32 vcc, 0, v3
	s_cbranch_vccnz .LBB0_1483
	v_readlane_b32 s4, v249, 1
	v_readlane_b32 s5, v249, 2
	s_load_dwordx2 s[2:3], s[4:5], 0x4
	s_add_u32 s4, s82, 0x4200
	s_addc_u32 s5, s83, 0
	s_add_u32 s6, s82, 0x4400
	s_addc_u32 s7, s83, 0
	s_add_u32 s8, s82, 0x4500
	s_addc_u32 s9, s83, 0
	s_add_u32 s10, s82, 0x4600
	s_addc_u32 s11, s83, 0
	s_add_u32 s12, s82, 0x4700
	s_addc_u32 s13, s83, 0
	s_add_u32 s14, s82, 0x4800
	s_addc_u32 s15, s83, 0
	s_add_u32 s16, s82, 0x4900
	s_addc_u32 s17, s83, 0
	s_add_u32 s18, s82, 0x4a00
	s_addc_u32 s19, s83, 0
	s_add_u32 s20, s82, 0x4b00
	s_addc_u32 s21, s83, 0
	s_add_u32 s22, s82, 0x4c00
	s_addc_u32 s23, s83, 0
	s_add_u32 s24, s82, 0x4d00
	s_addc_u32 s25, s83, 0
	s_add_u32 s26, s82, 0x4e00
	s_addc_u32 s27, s83, 0
	s_add_u32 s28, s82, 0x4f00
	s_addc_u32 s29, s83, 0
	s_add_u32 s30, s82, 0x5000
	s_addc_u32 s31, s83, 0
	s_add_u32 s34, s82, 0x5100
	s_addc_u32 s35, s83, 0
	s_add_u32 s36, s82, 0x5200
	s_addc_u32 s37, s83, 0
	s_waitcnt lgkmcnt(0)
	s_mul_i32 s2, s2, s90
	s_add_u32 s38, s82, 0x5300
	s_mul_i32 s2, s2, s3
	s_addc_u32 s39, s83, 0
	s_mov_b32 s3, 1
	v_mov_b32_e32 v17, 0
	s_branch .LBB0_1471

.Lnaep_4:
	s_barrier
.LBB0_1658:
	v_readlane_b32 s2, v249, 11
	v_readlane_b32 s3, v249, 12
	s_cmp_eq_u32 s3, 21
	s_cselect_b64 s[2:3], -1, 0
	s_or_b64 s[0:1], s[2:3], s[0:1]
	s_and_b64 vcc, exec, s[0:1]
	s_cbranch_vccnz .LBB0_1708
	s_waitcnt vmcnt(0)
	v_cmp_eq_u32_e32 vcc, 0, v0
	s_waitcnt vmcnt(0)
	s_barrier
	s_and_saveexec_b64 s[0:1], vcc
	s_cbranch_execz .LBB0_1707
	v_mov_b32_e32 v1, s87
	s_waitcnt vmcnt(0) expcnt(0) lgkmcnt(0)
	ds_read_b32 v3, v1
	ds_read_b32 v1, v1 offset:4
	s_waitcnt lgkmcnt(1)
	v_cmp_ne_u32_e32 vcc, 0, v3
	s_cbranch_vccnz .LBB0_1675
	v_readlane_b32 s4, v249, 1
	v_readlane_b32 s5, v249, 2
	s_load_dwordx2 s[2:3], s[4:5], 0x4
	s_add_u32 s4, s82, 0x4200
	s_addc_u32 s5, s83, 0
	s_add_u32 s6, s82, 0x4400
	s_addc_u32 s7, s83, 0
	s_add_u32 s8, s82, 0x4500
	s_addc_u32 s9, s83, 0
	s_add_u32 s10, s82, 0x4600
	s_addc_u32 s11, s83, 0
	s_add_u32 s12, s82, 0x4700
	s_addc_u32 s13, s83, 0
	s_add_u32 s14, s82, 0x4800
	s_addc_u32 s15, s83, 0
	s_add_u32 s16, s82, 0x4900
	s_addc_u32 s17, s83, 0
	s_add_u32 s18, s82, 0x4a00
	s_addc_u32 s19, s83, 0
	s_add_u32 s20, s82, 0x4b00
	s_addc_u32 s21, s83, 0
	s_add_u32 s22, s82, 0x4c00
	s_addc_u32 s23, s83, 0
	s_add_u32 s24, s82, 0x4d00
	s_addc_u32 s25, s83, 0
	s_add_u32 s26, s82, 0x4e00
	s_addc_u32 s27, s83, 0
	s_add_u32 s28, s82, 0x4f00
	s_addc_u32 s29, s83, 0
	s_add_u32 s30, s82, 0x5000
	s_addc_u32 s31, s83, 0
	s_add_u32 s34, s82, 0x5100
	s_addc_u32 s35, s83, 0
	s_add_u32 s36, s82, 0x5200
	s_addc_u32 s37, s83, 0
	s_waitcnt lgkmcnt(0)
	s_mul_i32 s2, s2, s90
	s_add_u32 s38, s82, 0x5300
	s_mul_i32 s2, s2, s3
	s_addc_u32 s39, s83, 0
	s_mov_b32 s3, 1
	v_mov_b32_e32 v17, 0
	s_branch .LBB0_1663

.Lnaep_3:
	s_barrier
.LBB0_1795:
	v_readlane_b32 s0, v249, 11
	v_readlane_b32 s1, v249, 12
	s_cmp_eq_u32 s1, 23
	s_cselect_b64 s[0:1], -1, 0
	s_or_b64 s[0:1], s[0:1], s[4:5]
	s_and_b64 vcc, exec, s[0:1]
	s_cbranch_vccnz .LBB0_1845
	s_waitcnt vmcnt(0)
	v_cmp_eq_u32_e32 vcc, 0, v0
	s_waitcnt vmcnt(0)
	s_barrier
	s_and_saveexec_b64 s[0:1], vcc
	s_cbranch_execz .LBB0_1844
	v_mov_b32_e32 v1, s87
	s_waitcnt vmcnt(0) expcnt(0) lgkmcnt(0)
	ds_read_b32 v3, v1
	ds_read_b32 v1, v1 offset:4
	s_waitcnt lgkmcnt(1)
	v_cmp_ne_u32_e32 vcc, 0, v3
	s_cbranch_vccnz .LBB0_1812
	v_readlane_b32 s4, v249, 1
	v_readlane_b32 s5, v249, 2
	s_load_dwordx2 s[2:3], s[4:5], 0x4
	s_add_u32 s4, s82, 0x4200
	s_addc_u32 s5, s83, 0
	s_add_u32 s6, s82, 0x4400
	s_addc_u32 s7, s83, 0
	s_add_u32 s8, s82, 0x4500
	s_addc_u32 s9, s83, 0
	s_add_u32 s10, s82, 0x4600
	s_addc_u32 s11, s83, 0
	s_add_u32 s12, s82, 0x4700
	s_addc_u32 s13, s83, 0
	s_add_u32 s14, s82, 0x4800
	s_addc_u32 s15, s83, 0
	s_add_u32 s16, s82, 0x4900
	s_addc_u32 s17, s83, 0
	s_add_u32 s18, s82, 0x4a00
	s_addc_u32 s19, s83, 0
	s_add_u32 s20, s82, 0x4b00
	s_addc_u32 s21, s83, 0
	s_add_u32 s22, s82, 0x4c00
	s_addc_u32 s23, s83, 0
	s_add_u32 s24, s82, 0x4d00
	s_addc_u32 s25, s83, 0
	s_add_u32 s26, s82, 0x4e00
	s_addc_u32 s27, s83, 0
	s_add_u32 s28, s82, 0x4f00
	s_addc_u32 s29, s83, 0
	s_add_u32 s30, s82, 0x5000
	s_addc_u32 s31, s83, 0
	s_add_u32 s34, s82, 0x5100
	s_addc_u32 s35, s83, 0
	s_add_u32 s36, s82, 0x5200
	s_addc_u32 s37, s83, 0
	s_waitcnt lgkmcnt(0)
	s_mul_i32 s2, s2, s90
	s_add_u32 s38, s82, 0x5300
	s_mul_i32 s2, s2, s3
	s_addc_u32 s39, s83, 0
	s_mov_b32 s3, 1
	v_mov_b32_e32 v17, 0
	s_branch .LBB0_1800

.Lnaep_2:
	s_barrier
.LBB0_2370:
	v_readlane_b32 s0, v249, 11
	v_readlane_b32 s1, v249, 12
	s_cmp_eq_u32 s1, 30
	s_cselect_b64 s[0:1], -1, 0
	s_or_b64 s[0:1], s[0:1], s[4:5]
	s_and_b64 vcc, exec, s[0:1]
	s_cbranch_vccnz .LBB0_2420
	s_waitcnt vmcnt(0)
	v_cmp_eq_u32_e32 vcc, 0, v0
	s_waitcnt vmcnt(0)
	s_barrier
	s_and_saveexec_b64 s[0:1], vcc
	s_cbranch_execz .LBB0_2419
	v_mov_b32_e32 v1, s87
	s_waitcnt vmcnt(0) expcnt(0) lgkmcnt(0)
	ds_read_b32 v3, v1
	ds_read_b32 v1, v1 offset:4
	s_waitcnt lgkmcnt(1)
	v_cmp_ne_u32_e32 vcc, 0, v3
	s_cbranch_vccnz .LBB0_2387
	v_readlane_b32 s4, v249, 1
	v_readlane_b32 s5, v249, 2
	s_load_dwordx2 s[2:3], s[4:5], 0x4
	s_add_u32 s4, s82, 0x4200
	s_addc_u32 s5, s83, 0
	s_add_u32 s6, s82, 0x4400
	s_addc_u32 s7, s83, 0
	s_add_u32 s8, s82, 0x4500
	s_addc_u32 s9, s83, 0
	s_add_u32 s10, s82, 0x4600
	s_addc_u32 s11, s83, 0
	s_add_u32 s12, s82, 0x4700
	s_addc_u32 s13, s83, 0
	s_add_u32 s14, s82, 0x4800
	s_addc_u32 s15, s83, 0
	s_add_u32 s16, s82, 0x4900
	s_addc_u32 s17, s83, 0
	s_add_u32 s18, s82, 0x4a00
	s_addc_u32 s19, s83, 0
	s_add_u32 s20, s82, 0x4b00
	s_addc_u32 s21, s83, 0
	s_add_u32 s22, s82, 0x4c00
	s_addc_u32 s23, s83, 0
	s_add_u32 s24, s82, 0x4d00
	s_addc_u32 s25, s83, 0
	s_add_u32 s26, s82, 0x4e00
	s_addc_u32 s27, s83, 0
	s_add_u32 s28, s82, 0x4f00
	s_addc_u32 s29, s83, 0
	s_add_u32 s30, s82, 0x5000
	s_addc_u32 s31, s83, 0
	s_add_u32 s34, s82, 0x5100
	s_addc_u32 s35, s83, 0
	s_add_u32 s36, s82, 0x5200
	s_addc_u32 s37, s83, 0
	s_waitcnt lgkmcnt(0)
	s_mul_i32 s2, s2, s90
	s_add_u32 s38, s82, 0x5300
	s_mul_i32 s2, s2, s3
	s_addc_u32 s39, s83, 0
	s_mov_b32 s3, 1
	v_mov_b32_e32 v17, 0
	s_branch .LBB0_2375

.Lnaep_1:
	s_barrier
.LBB0_2561:
	v_readlane_b32 s2, v249, 11
	v_readlane_b32 s3, v249, 12
	s_cmp_eq_u32 s3, 33
	s_cselect_b64 s[2:3], -1, 0
	s_or_b64 s[0:1], s[2:3], s[0:1]
	s_and_b64 vcc, exec, s[0:1]
	s_cbranch_vccnz .LBB0_2611
	s_waitcnt vmcnt(0)
	v_cmp_eq_u32_e32 vcc, 0, v0
	s_waitcnt vmcnt(0)
	s_barrier
	s_and_saveexec_b64 s[0:1], vcc
	s_cbranch_execz .LBB0_2610
	v_mov_b32_e32 v1, s87
	s_waitcnt vmcnt(0) expcnt(0) lgkmcnt(0)
	ds_read_b32 v3, v1
	ds_read_b32 v1, v1 offset:4
	s_waitcnt lgkmcnt(1)
	v_cmp_ne_u32_e32 vcc, 0, v3
	s_cbranch_vccnz .LBB0_2578
	v_readlane_b32 s4, v249, 1
	v_readlane_b32 s5, v249, 2
	s_load_dwordx2 s[2:3], s[4:5], 0x4
	s_add_u32 s4, s82, 0x4200
	s_addc_u32 s5, s83, 0
	s_add_u32 s6, s82, 0x4400
	s_addc_u32 s7, s83, 0
	s_add_u32 s8, s82, 0x4500
	s_addc_u32 s9, s83, 0
	s_add_u32 s10, s82, 0x4600
	s_addc_u32 s11, s83, 0
	s_add_u32 s12, s82, 0x4700
	s_addc_u32 s13, s83, 0
	s_add_u32 s14, s82, 0x4800
	s_addc_u32 s15, s83, 0
	s_add_u32 s16, s82, 0x4900
	s_addc_u32 s17, s83, 0
	s_add_u32 s18, s82, 0x4a00
	s_addc_u32 s19, s83, 0
	s_add_u32 s20, s82, 0x4b00
	s_addc_u32 s21, s83, 0
	s_add_u32 s22, s82, 0x4c00
	s_addc_u32 s23, s83, 0
	s_add_u32 s24, s82, 0x4d00
	s_addc_u32 s25, s83, 0
	s_add_u32 s26, s82, 0x4e00
	s_addc_u32 s27, s83, 0
	s_add_u32 s28, s82, 0x4f00
	s_addc_u32 s29, s83, 0
	s_add_u32 s30, s82, 0x5000
	s_addc_u32 s31, s83, 0
	s_add_u32 s34, s82, 0x5100
	s_addc_u32 s35, s83, 0
	s_add_u32 s36, s82, 0x5200
	s_addc_u32 s37, s83, 0
	s_waitcnt lgkmcnt(0)
	s_mul_i32 s2, s2, s90
	s_add_u32 s38, s82, 0x5300
	s_mul_i32 s2, s2, s3
	s_addc_u32 s39, s83, 0
	s_mov_b32 s3, 1
	v_mov_b32_e32 v17, 0
	s_branch .LBB0_2566

.Lnaep_0:
	s_barrier
.LBB0_2698:
	v_readlane_b32 s0, v249, 11
	v_readlane_b32 s1, v249, 12
	s_cmp_eq_u32 s1, 35
	s_cselect_b64 s[0:1], -1, 0
	s_or_b64 s[0:1], s[0:1], s[4:5]
	s_and_b64 vcc, exec, s[0:1]
	s_cbranch_vccnz .LBB0_2748
	s_waitcnt vmcnt(0)
	v_cmp_eq_u32_e32 vcc, 0, v0
	s_waitcnt vmcnt(0)
	s_barrier
	s_and_saveexec_b64 s[0:1], vcc
	s_cbranch_execz .LBB0_2747
	v_mov_b32_e32 v1, s87
	s_waitcnt vmcnt(0) expcnt(0) lgkmcnt(0)
	ds_read_b32 v3, v1
	ds_read_b32 v1, v1 offset:4
	s_waitcnt lgkmcnt(1)
	v_cmp_ne_u32_e32 vcc, 0, v3
	s_cbranch_vccnz .LBB0_2715
	v_readlane_b32 s4, v249, 1
	v_readlane_b32 s5, v249, 2
	s_load_dwordx2 s[2:3], s[4:5], 0x4
	s_add_u32 s4, s82, 0x4200
	s_addc_u32 s5, s83, 0
	s_add_u32 s6, s82, 0x4400
	s_addc_u32 s7, s83, 0
	s_add_u32 s8, s82, 0x4500
	s_addc_u32 s9, s83, 0
	s_add_u32 s10, s82, 0x4600
	s_addc_u32 s11, s83, 0
	s_add_u32 s12, s82, 0x4700
	s_addc_u32 s13, s83, 0
	s_add_u32 s14, s82, 0x4800
	s_addc_u32 s15, s83, 0
	s_add_u32 s16, s82, 0x4900
	s_addc_u32 s17, s83, 0
	s_add_u32 s18, s82, 0x4a00
	s_addc_u32 s19, s83, 0
	s_add_u32 s20, s82, 0x4b00
	s_addc_u32 s21, s83, 0
	s_add_u32 s22, s82, 0x4c00
	s_addc_u32 s23, s83, 0
	s_add_u32 s24, s82, 0x4d00
	s_addc_u32 s25, s83, 0
	s_add_u32 s26, s82, 0x4e00
	s_addc_u32 s27, s83, 0
	s_add_u32 s28, s82, 0x4f00
	s_addc_u32 s29, s83, 0
	s_add_u32 s30, s82, 0x5000
	s_addc_u32 s31, s83, 0
	s_add_u32 s34, s82, 0x5100
	s_addc_u32 s35, s83, 0
	s_add_u32 s36, s82, 0x5200
	s_addc_u32 s37, s83, 0
	s_waitcnt lgkmcnt(0)
	s_mul_i32 s2, s2, s90
	s_add_u32 s38, s82, 0x5300
	s_mul_i32 s2, s2, s3
	s_addc_u32 s39, s83, 0
	s_mov_b32 s3, 1
	v_mov_b32_e32 v17, 0
	s_branch .LBB0_2703
